# U-pass loop: wait vmcnt(17) instead of vmcnt(0) after issuing next prefetch set
# baseline (speedup 1.0000x reference)
.LBB0_926:
	s_add_i32 s67, s0, 2
	s_cmpk_gt_u32 s0, 0xfd
	s_cselect_b64 s[0:1], -1, 0
	s_and_b64 vcc, exec, s[0:1]
	ds_write_b64 v138, v[178:179]
	s_cbranch_vccnz .LBB0_928
	s_and_b32 s17, s61, 0x700
	v_lshl_add_u32 v0, s17, 2, v189
	ds_read_b128 v[6:9], v0
	ds_read_b128 v[22:25], v0 offset:16
	ds_read_b128 v[38:41], v0 offset:32
	ds_read_b128 v[54:57], v0 offset:48
	v_and_or_b32 v64, s67, 14, v176
	s_and_b32 s16, s59, 0x3e00000
	v_ashrrev_i32_e32 v65, 31, v64
	s_add_u32 s16, s36, s16
	v_lshlrev_b64 v[64:65], 11, v[64:65]
	s_addc_u32 s17, s37, 0
	v_lshl_add_u64 v[64:65], s[30:31], 0, v[64:65]
	s_and_b32 s34, s63, 0xf80
	s_waitcnt lgkmcnt(3)
	v_lshlrev_b32_e32 v0, 7, v7
	v_lshlrev_b32_e32 v1, 7, v6
	v_lshlrev_b32_e32 v9, 7, v9
	v_lshlrev_b32_e32 v8, 7, v8
	s_waitcnt lgkmcnt(2)
	v_lshlrev_b32_e32 v16, 7, v23
	v_lshlrev_b32_e32 v17, 7, v22
	v_lshlrev_b32_e32 v25, 7, v25
	v_lshlrev_b32_e32 v24, 7, v24
	s_waitcnt lgkmcnt(1)
	v_lshlrev_b32_e32 v32, 7, v39
	v_lshlrev_b32_e32 v33, 7, v38
	v_lshlrev_b32_e32 v41, 7, v41
	v_lshlrev_b32_e32 v40, 7, v40
	s_waitcnt lgkmcnt(0)
	v_lshlrev_b32_e32 v48, 7, v55
	v_lshlrev_b32_e32 v49, 7, v54
	v_lshlrev_b32_e32 v57, 7, v57
	v_lshlrev_b32_e32 v56, 7, v56
	v_lshl_add_u64 v[64:65], v[64:65], 0, s[34:35]
	v_or_b32_e32 v4, v0, v137
	v_or_b32_e32 v0, v1, v174
	v_or_b32_e32 v12, v9, v137
	v_or_b32_e32 v8, v8, v174
	v_or_b32_e32 v20, v16, v137
	v_or_b32_e32 v16, v17, v174
	v_or_b32_e32 v28, v25, v137
	v_or_b32_e32 v24, v24, v174
	v_or_b32_e32 v36, v32, v137
	v_or_b32_e32 v32, v33, v174
	v_or_b32_e32 v44, v41, v137
	v_or_b32_e32 v40, v40, v174
	v_or_b32_e32 v52, v48, v137
	v_or_b32_e32 v48, v49, v174
	v_or_b32_e32 v60, v57, v137
	v_or_b32_e32 v56, v56, v174
	v_lshl_add_u64 v[64:65], v[64:65], 0, v[142:143]
	global_load_dwordx4 v[0:3], v0, s[16:17]
	s_nop 0
	global_load_dwordx4 v[4:7], v4, s[16:17]
	s_nop 0
	global_load_dwordx4 v[8:11], v8, s[16:17]
	s_nop 0
	global_load_dwordx4 v[12:15], v12, s[16:17]
	s_nop 0
	global_load_dwordx4 v[16:19], v16, s[16:17]
	s_nop 0
	global_load_dwordx4 v[20:23], v20, s[16:17]
	s_nop 0
	global_load_dwordx4 v[24:27], v24, s[16:17]
	s_nop 0
	global_load_dwordx4 v[28:31], v28, s[16:17]
	s_nop 0
	global_load_dwordx4 v[32:35], v32, s[16:17]
	s_nop 0
	global_load_dwordx4 v[36:39], v36, s[16:17]
	s_nop 0
	global_load_dwordx4 v[40:43], v40, s[16:17]
	s_nop 0
	global_load_dwordx4 v[44:47], v44, s[16:17]
	s_nop 0
	global_load_dwordx4 v[48:51], v48, s[16:17]
	s_nop 0
	global_load_dwordx4 v[52:55], v52, s[16:17]
	s_nop 0
	global_load_dwordx4 v[56:59], v56, s[16:17]
	s_nop 0
	global_load_dwordx4 v[60:63], v60, s[16:17]
	s_nop 0
	global_load_dwordx4 v[64:67], v[64:65], off
	s_waitcnt vmcnt(17)
	s_branch .Lu_setb_ready
.LBB0_928:
	s_waitcnt vmcnt(0)
.Lu_setb_ready:
	v_mov_b32_e32 v138, v139
	v_dot4c_i32_i8_e32 v138, v132, v80
	v_mov_b32_e32 v132, v139
	v_dot4c_i32_i8_e32 v132, v128, v80
	v_mov_b32_e32 v128, v139
	v_dot4c_i32_i8_e32 v128, v124, v80
	v_mov_b32_e32 v124, v139
	v_dot4c_i32_i8_e32 v124, v120, v80
	v_mov_b32_e32 v120, v139
	v_dot4c_i32_i8_e32 v120, v116, v80
	v_mov_b32_e32 v116, v139
	v_dot4c_i32_i8_e32 v116, v112, v80
	v_mov_b32_e32 v112, v139
	v_dot4c_i32_i8_e32 v112, v108, v80
	v_mov_b32_e32 v108, v139
	v_dot4c_i32_i8_e32 v108, v104, v80
	v_mov_b32_e32 v104, v139
	v_dot4c_i32_i8_e32 v104, v100, v80
	v_mov_b32_e32 v100, v139
	v_dot4c_i32_i8_e32 v100, v96, v80
	v_mov_b32_e32 v96, v139
	v_dot4c_i32_i8_e32 v96, v92, v80
	v_mov_b32_e32 v92, v139
	v_dot4c_i32_i8_e32 v92, v88, v80
	v_mov_b32_e32 v88, v139
	v_dot4c_i32_i8_e32 v88, v84, v80
	v_mov_b32_e32 v84, v139
	v_dot4c_i32_i8_e32 v138, v133, v81
	v_dot4c_i32_i8_e32 v104, v101, v81
	v_dot4c_i32_i8_e32 v84, v76, v80
	v_mov_b32_e32 v76, v139
	v_dot4c_i32_i8_e32 v138, v134, v82
	v_dot4c_i32_i8_e32 v132, v129, v81
	v_dot4c_i32_i8_e32 v104, v102, v82
	v_dot4c_i32_i8_e32 v100, v97, v81
	v_dot4c_i32_i8_e32 v76, v72, v80
	v_mov_b32_e32 v72, v139
	v_dot4c_i32_i8_e32 v138, v135, v83
	v_dot4c_i32_i8_e32 v132, v130, v82
	v_dot4c_i32_i8_e32 v128, v125, v81
	v_dot4c_i32_i8_e32 v104, v103, v83
	v_dot4c_i32_i8_e32 v100, v98, v82
	v_dot4c_i32_i8_e32 v96, v93, v81
	v_dot4c_i32_i8_e32 v72, v68, v80
	v_dot4c_i32_i8_e32 v132, v131, v83
	v_dot4c_i32_i8_e32 v128, v126, v82
	v_dot4c_i32_i8_e32 v124, v121, v81
	v_dot4c_i32_i8_e32 v100, v99, v83
	v_dot4c_i32_i8_e32 v96, v94, v82
	v_dot4c_i32_i8_e32 v92, v89, v81
	v_dot4c_i32_i8_e32 v72, v69, v81
	v_cndmask_b32_e64 v69, v138, v104, s[2:3]
	v_dot4c_i32_i8_e32 v128, v127, v83
	v_dot4c_i32_i8_e32 v124, v122, v82
	v_dot4c_i32_i8_e32 v120, v117, v81
	v_dot4c_i32_i8_e32 v96, v95, v83
	v_dot4c_i32_i8_e32 v92, v90, v82
	v_dot4c_i32_i8_e32 v88, v85, v81
	v_dot4c_i32_i8_e32 v72, v70, v82
	ds_bpermute_b32 v69, v201, v69
	v_cndmask_b32_e64 v70, v132, v100, s[2:3]
	v_dot4c_i32_i8_e32 v124, v123, v83
	v_dot4c_i32_i8_e32 v120, v118, v82
	v_dot4c_i32_i8_e32 v116, v113, v81
	v_dot4c_i32_i8_e32 v92, v91, v83
	v_dot4c_i32_i8_e32 v88, v86, v82
	v_dot4c_i32_i8_e32 v84, v77, v81
	v_dot4c_i32_i8_e32 v72, v71, v83
	ds_bpermute_b32 v70, v201, v70
	v_cndmask_b32_e64 v71, v128, v96, s[2:3]
	v_dot4c_i32_i8_e32 v120, v119, v83
	v_dot4c_i32_i8_e32 v116, v114, v82
	v_dot4c_i32_i8_e32 v88, v87, v83
	v_dot4c_i32_i8_e32 v84, v78, v82
	v_dot4c_i32_i8_e32 v76, v73, v81
	ds_bpermute_b32 v71, v201, v71
	v_cndmask_b32_e64 v73, v124, v92, s[2:3]
	v_dot4c_i32_i8_e32 v116, v115, v83
	v_dot4c_i32_i8_e32 v84, v79, v83
	v_dot4c_i32_i8_e32 v76, v74, v82
	ds_bpermute_b32 v73, v201, v73
	v_cndmask_b32_e64 v74, v120, v88, s[2:3]
	v_dot4c_i32_i8_e32 v76, v75, v83
	v_cndmask_b32_e64 v68, v104, v138, s[2:3]
	ds_bpermute_b32 v74, v201, v74
	v_cndmask_b32_e64 v75, v116, v84, s[2:3]
	s_waitcnt lgkmcnt(4)
	v_add_u32_e32 v68, v69, v68
	v_cndmask_b32_e64 v69, v100, v132, s[2:3]
	ds_bpermute_b32 v75, v201, v75
	s_waitcnt lgkmcnt(4)
	v_add_u32_e32 v69, v70, v69
	v_cndmask_b32_e64 v70, v96, v128, s[2:3]
	v_dot4c_i32_i8_e32 v112, v109, v81
	v_dot4c_i32_i8_e32 v108, v105, v81
	s_waitcnt lgkmcnt(3)
	v_add_u32_e32 v70, v71, v70
	v_cndmask_b32_e64 v71, v92, v124, s[2:3]
	v_dot4c_i32_i8_e32 v112, v110, v82
	v_dot4c_i32_i8_e32 v108, v106, v82
	s_waitcnt lgkmcnt(2)
	v_add_u32_e32 v71, v73, v71
	v_cndmask_b32_e64 v73, v88, v120, s[2:3]
	v_dot4c_i32_i8_e32 v112, v111, v83
	v_dot4c_i32_i8_e32 v108, v107, v83
	s_waitcnt lgkmcnt(1)
	v_add_u32_e32 v73, v74, v73
	v_cndmask_b32_e64 v74, v84, v116, s[2:3]
	s_waitcnt lgkmcnt(0)
	v_add_u32_e32 v74, v75, v74
	v_cndmask_b32_e64 v75, v76, v112, s[2:3]
	v_cndmask_b32_e64 v76, v112, v76, s[2:3]
	v_cndmask_b32_e64 v77, v108, v72, s[2:3]
	ds_bpermute_b32 v76, v201, v76
	ds_bpermute_b32 v77, v201, v77
	v_cndmask_b32_e64 v72, v72, v108, s[2:3]
	v_cndmask_b32_e64 v78, v68, v73, s[4:5]
	v_cndmask_b32_e64 v68, v73, v68, s[4:5]
	s_waitcnt lgkmcnt(1)
	v_add_u32_e32 v75, v76, v75
	s_waitcnt lgkmcnt(0)
	v_add_u32_e32 v72, v77, v72
	v_cndmask_b32_e64 v73, v74, v69, s[4:5]
	v_cndmask_b32_e64 v69, v69, v74, s[4:5]
	v_cndmask_b32_e64 v74, v70, v75, s[4:5]
	v_cndmask_b32_e64 v76, v71, v72, s[4:5]
	ds_bpermute_b32 v78, v202, v78
	ds_bpermute_b32 v69, v202, v69
	ds_bpermute_b32 v74, v202, v74
	ds_bpermute_b32 v76, v202, v76
	v_cndmask_b32_e64 v70, v75, v70, s[4:5]
	v_cndmask_b32_e64 v71, v72, v71, s[4:5]
	s_waitcnt lgkmcnt(3)
	v_add_u32_e32 v68, v78, v68
	s_waitcnt lgkmcnt(2)
	v_add_u32_e32 v69, v69, v73
	s_waitcnt lgkmcnt(1)
	v_add_u32_e32 v70, v74, v70
	s_waitcnt lgkmcnt(0)
	v_add_u32_e32 v71, v76, v71
	v_cndmask_b32_e64 v72, v68, v70, s[6:7]
	v_cndmask_b32_e64 v73, v69, v71, s[6:7]
	ds_bpermute_b32 v72, v203, v72
	ds_bpermute_b32 v73, v203, v73
	v_cndmask_b32_e64 v68, v70, v68, s[6:7]
	v_cndmask_b32_e64 v69, v71, v69, s[6:7]
	s_andn2_b64 vcc, exec, s[14:15]
	s_waitcnt lgkmcnt(1)
	v_add_u32_e32 v68, v72, v68
	s_waitcnt lgkmcnt(0)
	v_add_u32_e32 v69, v73, v69
	v_lshl_add_u32 v70, s65, 2, v190
	s_cbranch_vccnz .LBB0_923
	ds_read_b64 v[72:73], v70
	s_waitcnt lgkmcnt(0)
	v_add_u32_e32 v68, v72, v68
	v_add_u32_e32 v69, v73, v69
	s_branch .LBB0_923
